# pool/conv RMSNorm wave reductions via DPP (xor 1/2/4/8) and permlane16/32 swaps instead of six ds_bpermute round trips
# speedup vs baseline: 1.0122x; 1.0065x over previous
.LBB0_562:
	s_or_b64 exec, exec, s[12:13]
	v_cvt_f32_i32_e32 v2, v38
	v_sub_f32_e32 v1, v170, v165
	v_ashrrev_i32_e32 v37, 31, v36
	v_cmp_lt_i32_e32 vcc, v223, v222
	v_rcp_iflag_f32_e32 v2, v2
	s_add_i32 s12, s59, s41
	s_ashr_i32 s13, s12, 31
	s_lshl_b64 s[12:13], s[12:13], 11
	v_fma_f32 v1, v3, v2, -v1
	v_lshlrev_b64 v[2:3], 11, v[36:37]
	v_cvt_pk_bf16_f32 v1, v1, s0
	v_lshl_add_u64 v[2:3], v[44:45], 0, v[2:3]
	global_store_short v[2:3], v1, off
	s_waitcnt lgkmcnt(0)
	s_barrier
	v_add_u32_e32 v2, s35, v140
	ds_read_b128 v[112:115], v2 offset:56320
	v_cndmask_b32_e32 v1, v221, v223, vcc
	v_lshlrev_b32_e32 v110, 2, v1
	v_cmp_lt_i32_e32 vcc, v224, v222
	v_lshl_add_u64 v[104:105], v[102:103], 0, s[12:13]
	s_waitcnt lgkmcnt(0)
	v_pk_mul_f32 v[2:3], v[114:115], v[114:115]
	v_pk_mul_f32 v[36:37], v[112:113], v[112:113]
	v_cndmask_b32_e32 v1, v221, v224, vcc
	v_pk_mov_b32 v[38:39], v[36:37], v[2:3] op_sel:[1,0]
	v_mov_b32_e32 v37, v3
	v_pk_add_f32 v[2:3], v[38:39], v[36:37]
	v_add_u32_e32 v36, s45, v140
	ds_read_b128 v[36:39], v36 offset:56320
	v_lshlrev_b32_e32 v109, 2, v1
	v_cmp_lt_i32_e32 vcc, v225, v222
	s_waitcnt lgkmcnt(0)
	v_pk_mul_f32 v[116:117], v[38:39], v[38:39]
	v_pk_mul_f32 v[118:119], v[36:37], v[36:37]
	v_cndmask_b32_e32 v1, v221, v225, vcc
	v_pk_mov_b32 v[120:121], v[118:119], v[116:117] op_sel:[1,0]
	v_mov_b32_e32 v119, v117
	v_pk_add_f32 v[116:117], v[120:121], v[118:119]
	v_mov_b32_e32 v119, v2
	v_mov_b32_e32 v118, v116
	v_mov_b32_e32 v2, v117
	v_pk_add_f32 v[2:3], v[118:119], v[2:3]
	s_nop 1
	v_mov_b32_dpp v117, v3 quad_perm:[1,0,3,2] row_mask:0xf bank_mask:0xf
	v_mov_b32_dpp v116, v2 quad_perm:[1,0,3,2] row_mask:0xf bank_mask:0xf
	v_lshlrev_b32_e32 v108, 2, v1
	v_cmp_lt_i32_e32 vcc, v226, v222
	s_waitcnt lgkmcnt(0)
	v_pk_add_f32 v[2:3], v[2:3], v[116:117]
	s_nop 1
	v_mov_b32_dpp v117, v3 quad_perm:[2,3,0,1] row_mask:0xf bank_mask:0xf
	v_mov_b32_dpp v116, v2 quad_perm:[2,3,0,1] row_mask:0xf bank_mask:0xf
	v_cndmask_b32_e32 v1, v221, v226, vcc
	v_lshlrev_b32_e32 v107, 2, v1
	v_cmp_lt_i32_e32 vcc, v227, v222
	s_waitcnt lgkmcnt(0)
	v_pk_add_f32 v[2:3], v[2:3], v[116:117]
	s_nop 1
	v_mov_b32_dpp v117, v3 row_half_mirror row_mask:0xf bank_mask:0xf
	v_mov_b32_dpp v116, v2 row_half_mirror row_mask:0xf bank_mask:0xf
	v_cndmask_b32_e32 v1, v221, v227, vcc
	v_lshlrev_b32_e32 v106, 2, v1
	v_cmp_lt_i32_e32 vcc, v228, v222
	s_waitcnt lgkmcnt(0)
	v_pk_add_f32 v[2:3], v[2:3], v[116:117]
	s_nop 1
	v_mov_b32_dpp v117, v3 row_mirror row_mask:0xf bank_mask:0xf
	v_mov_b32_dpp v116, v2 row_mirror row_mask:0xf bank_mask:0xf
	v_cndmask_b32_e32 v1, v221, v228, vcc
	v_lshlrev_b32_e32 v1, 2, v1
	s_waitcnt lgkmcnt(0)
	v_pk_add_f32 v[2:3], v[2:3], v[116:117]
	s_nop 1
	v_mov_b32_e32 v117, v3
	s_nop 1
	v_permlane16_swap_b32_e32 v117, v3
	v_mov_b32_e32 v116, v2
	s_nop 1
	v_permlane16_swap_b32_e32 v116, v2
	s_waitcnt lgkmcnt(0)
	v_pk_add_f32 v[2:3], v[2:3], v[116:117]
	s_nop 1
	v_mov_b32_e32 v117, v3
	s_nop 1
	v_permlane32_swap_b32_e32 v117, v3
	v_mov_b32_e32 v116, v2
	s_nop 1
	v_permlane32_swap_b32_e32 v116, v2
	s_waitcnt lgkmcnt(0)
	v_pk_add_f32 v[116:117], v[2:3], v[116:117]
	v_mov_b64_e32 v[2:3], s[64:65]
	v_pk_fma_f32 v[116:117], v[116:117], s[80:81], v[2:3] op_sel_hi:[1,0,0]
	s_nop 0
	v_mul_f32_e32 v111, 0x4b800000, v117
	v_cmp_gt_f32_e64 s[12:13], s92, v117
	v_cmp_gt_f32_e32 vcc, s92, v116
	s_nop 0
	v_cndmask_b32_e64 v111, v117, v111, s[12:13]
	v_rsq_f32_e32 v111, v111
	s_nop 0
	v_mul_f32_e32 v117, 0x45800000, v111
	v_cndmask_b32_e64 v118, v111, v117, s[12:13]
	v_pk_mul_f32 v[112:113], v[112:113], v[118:119] op_sel_hi:[1,0]
	v_pk_mul_f32 v[114:115], v[114:115], v[118:119] op_sel_hi:[1,0]
	v_pk_mul_f32 v[112:113], v[20:21], v[112:113]
	v_pk_mul_f32 v[114:115], v[22:23], v[114:115]
	v_mul_f32_e32 v111, 0xbfb8aa3b, v112
	v_exp_f32_e32 v111, v111
	s_add_i32 s12, s59, s44
	s_ashr_i32 s13, s12, 31
	s_lshl_b64 s[12:13], s[12:13], 11
	v_add_f32_e32 v111, 1.0, v111
	v_rcp_f32_e32 v118, v111
	v_mul_f32_e32 v111, 0xbfb8aa3b, v113
	v_exp_f32_e32 v111, v111
	s_nop 0
	v_add_f32_e32 v111, 1.0, v111
	v_rcp_f32_e32 v119, v111
	v_mul_f32_e32 v111, 0xbfb8aa3b, v114
	v_exp_f32_e32 v111, v111
	v_pk_mul_f32 v[112:113], v[112:113], v[118:119]
	s_nop 0
	v_cvt_pk_bf16_f32 v112, v112, v113
	v_add_f32_e32 v111, 1.0, v111
	v_rcp_f32_e32 v118, v111
	v_mul_f32_e32 v111, 0xbfb8aa3b, v115
	v_exp_f32_e32 v111, v111
	s_nop 0
	v_add_f32_e32 v111, 1.0, v111
	v_rcp_f32_e32 v119, v111
	s_nop 0
	v_pk_mul_f32 v[114:115], v[114:115], v[118:119]
	s_nop 0
	v_cvt_pk_bf16_f32 v113, v114, v115
	global_store_dwordx2 v[104:105], v[112:113], off offset:512
	v_mul_f32_e32 v104, 0x4b800000, v116
	v_cndmask_b32_e32 v104, v116, v104, vcc
	v_rsq_f32_e32 v104, v104
	s_nop 0
	v_mul_f32_e32 v105, 0x45800000, v104
	v_cndmask_b32_e32 v104, v104, v105, vcc
	v_pk_mul_f32 v[36:37], v[36:37], v[104:105] op_sel_hi:[1,0]
	v_pk_mul_f32 v[38:39], v[38:39], v[104:105] op_sel_hi:[1,0]
	v_pk_mul_f32 v[36:37], v[20:21], v[36:37]
	v_pk_mul_f32 v[38:39], v[22:23], v[38:39]
	v_mul_f32_e32 v104, 0xbfb8aa3b, v36
	v_mul_f32_e32 v105, 0xbfb8aa3b, v37
	v_exp_f32_e32 v104, v104
	v_exp_f32_e32 v105, v105
	v_add_f32_e32 v104, 1.0, v104
	v_add_f32_e32 v105, 1.0, v105
	v_rcp_f32_e32 v104, v104
	v_rcp_f32_e32 v105, v105
	s_nop 0
	v_pk_mul_f32 v[36:37], v[36:37], v[104:105]
	v_mul_f32_e32 v104, 0xbfb8aa3b, v38
	v_mul_f32_e32 v105, 0xbfb8aa3b, v39
	v_exp_f32_e32 v104, v104
	v_exp_f32_e32 v105, v105
	v_cvt_pk_bf16_f32 v36, v36, v37
	v_add_f32_e32 v104, 1.0, v104
	v_add_f32_e32 v105, 1.0, v105
	v_rcp_f32_e32 v104, v104
	v_rcp_f32_e32 v105, v105
	s_nop 0
	v_pk_mul_f32 v[38:39], v[38:39], v[104:105]
	s_nop 0
	v_cvt_pk_bf16_f32 v37, v38, v39
	v_lshl_add_u64 v[38:39], v[102:103], 0, s[12:13]
	global_store_dwordx2 v[38:39], v[36:37], off offset:512
	v_add_u32_e32 v36, s56, v140
	ds_read_b128 v[112:115], v36 offset:56320
	s_add_i32 s12, s59, s46
	s_ashr_i32 s13, s12, 31
	s_lshl_b64 s[12:13], s[12:13], 11
	s_waitcnt lgkmcnt(0)
	v_pk_mul_f32 v[36:37], v[114:115], v[114:115]
	v_pk_mul_f32 v[38:39], v[112:113], v[112:113]
	s_nop 0
	v_pk_mov_b32 v[104:105], v[38:39], v[36:37] op_sel:[1,0]
	v_mov_b32_e32 v39, v37
	v_add_u32_e32 v36, s58, v140
	v_pk_add_f32 v[116:117], v[104:105], v[38:39]
	ds_read_b128 v[36:39], v36 offset:56320
	v_lshl_add_u64 v[104:105], v[102:103], 0, s[12:13]
	s_waitcnt lgkmcnt(0)
	v_pk_mul_f32 v[118:119], v[38:39], v[38:39]
	v_pk_mul_f32 v[120:121], v[36:37], v[36:37]
	s_nop 0
	v_pk_mov_b32 v[122:123], v[120:121], v[118:119] op_sel:[1,0]
	v_mov_b32_e32 v121, v119
	v_pk_add_f32 v[118:119], v[122:123], v[120:121]
	v_mov_b32_e32 v121, v116
	v_mov_b32_e32 v120, v118
	v_mov_b32_e32 v116, v119
	v_pk_add_f32 v[116:117], v[120:121], v[116:117]
	s_nop 1
	v_mov_b32_dpp v111, v117 quad_perm:[1,0,3,2] row_mask:0xf bank_mask:0xf
	v_mov_b32_dpp v110, v116 quad_perm:[1,0,3,2] row_mask:0xf bank_mask:0xf
	s_waitcnt lgkmcnt(0)
	v_pk_add_f32 v[110:111], v[116:117], v[110:111]
	s_nop 1
	v_mov_b32_dpp v117, v111 quad_perm:[2,3,0,1] row_mask:0xf bank_mask:0xf
	v_mov_b32_dpp v116, v110 quad_perm:[2,3,0,1] row_mask:0xf bank_mask:0xf
	s_waitcnt lgkmcnt(0)
	v_pk_add_f32 v[110:111], v[110:111], v[116:117]
	s_nop 1
	v_mov_b32_dpp v109, v111 row_half_mirror row_mask:0xf bank_mask:0xf
	v_mov_b32_dpp v108, v110 row_half_mirror row_mask:0xf bank_mask:0xf
	s_waitcnt lgkmcnt(0)
	v_pk_add_f32 v[108:109], v[110:111], v[108:109]
	s_nop 1
	v_mov_b32_dpp v111, v109 row_mirror row_mask:0xf bank_mask:0xf
	v_mov_b32_dpp v110, v108 row_mirror row_mask:0xf bank_mask:0xf
	s_waitcnt lgkmcnt(0)
	v_pk_add_f32 v[108:109], v[108:109], v[110:111]
	s_nop 1
	v_mov_b32_e32 v107, v109
	s_nop 1
	v_permlane16_swap_b32_e32 v107, v109
	v_mov_b32_e32 v106, v108
	s_nop 1
	v_permlane16_swap_b32_e32 v106, v108
	s_waitcnt lgkmcnt(0)
	v_pk_add_f32 v[106:107], v[108:109], v[106:107]
	s_nop 1
	v_mov_b32_e32 v109, v107
	s_nop 1
	v_permlane32_swap_b32_e32 v109, v107
	v_mov_b32_e32 v108, v106
	s_nop 1
	v_permlane32_swap_b32_e32 v108, v106
	s_waitcnt lgkmcnt(0)
	v_pk_add_f32 v[106:107], v[106:107], v[108:109]
	s_nop 0
	v_pk_fma_f32 v[2:3], v[106:107], s[80:81], v[2:3] op_sel_hi:[1,0,0]
	s_nop 0
	v_mul_f32_e32 v1, 0x4b800000, v3
	v_cmp_gt_f32_e64 s[12:13], s92, v3
	v_cmp_gt_f32_e32 vcc, s92, v2
	s_nop 0
	v_cndmask_b32_e64 v1, v3, v1, s[12:13]
	v_rsq_f32_e32 v1, v1
	s_nop 0
	v_mul_f32_e32 v3, 0x45800000, v1
	v_cndmask_b32_e64 v106, v1, v3, s[12:13]
	v_pk_mul_f32 v[108:109], v[112:113], v[106:107] op_sel_hi:[1,0]
	v_pk_mul_f32 v[106:107], v[114:115], v[106:107] op_sel_hi:[1,0]
	v_pk_mul_f32 v[108:109], v[20:21], v[108:109]
	v_pk_mul_f32 v[106:107], v[22:23], v[106:107]
	v_mul_f32_e32 v1, 0xbfb8aa3b, v108
	v_exp_f32_e32 v1, v1
	s_add_i32 s12, s59, s57
	s_ashr_i32 s13, s12, 31
	s_lshl_b64 s[12:13], s[12:13], 11
	v_add_f32_e32 v1, 1.0, v1
	v_rcp_f32_e32 v110, v1
	v_mul_f32_e32 v1, 0xbfb8aa3b, v109
	v_exp_f32_e32 v1, v1
	s_cmp_eq_u32 s40, s81
	v_add_f32_e32 v1, 1.0, v1
	v_rcp_f32_e32 v111, v1
	v_mul_f32_e32 v1, 0xbfb8aa3b, v106
	v_exp_f32_e32 v1, v1
	v_pk_mul_f32 v[108:109], v[108:109], v[110:111]
	s_nop 0
	v_cvt_pk_bf16_f32 v108, v108, v109
	v_add_f32_e32 v1, 1.0, v1
	v_rcp_f32_e32 v110, v1
	v_mul_f32_e32 v1, 0xbfb8aa3b, v107
	v_exp_f32_e32 v1, v1
	s_nop 0
	v_add_f32_e32 v1, 1.0, v1
	v_rcp_f32_e32 v111, v1
	v_mul_f32_e32 v1, 0x4b800000, v2
	v_cndmask_b32_e32 v1, v2, v1, vcc
	v_rsq_f32_e32 v1, v1
	v_pk_mul_f32 v[106:107], v[106:107], v[110:111]
	v_mul_f32_e32 v2, 0x45800000, v1
	v_cndmask_b32_e32 v2, v1, v2, vcc
	v_pk_mul_f32 v[36:37], v[36:37], v[2:3] op_sel_hi:[1,0]
	v_pk_mul_f32 v[2:3], v[38:39], v[2:3] op_sel_hi:[1,0]
	v_pk_mul_f32 v[36:37], v[20:21], v[36:37]
	v_pk_mul_f32 v[2:3], v[22:23], v[2:3]
	v_mul_f32_e32 v1, 0xbfb8aa3b, v36
	v_exp_f32_e32 v1, v1
	v_cvt_pk_bf16_f32 v109, v106, v107
	global_store_dwordx2 v[104:105], v[108:109], off offset:512
	v_add_f32_e32 v1, 1.0, v1
	v_rcp_f32_e32 v38, v1
	v_mul_f32_e32 v1, 0xbfb8aa3b, v37
	v_exp_f32_e32 v1, v1
	s_nop 0
	v_add_f32_e32 v1, 1.0, v1
	v_rcp_f32_e32 v39, v1
	v_mul_f32_e32 v1, 0xbfb8aa3b, v2
	v_exp_f32_e32 v1, v1
	v_pk_mul_f32 v[36:37], v[36:37], v[38:39]
	s_nop 0
	v_cvt_pk_bf16_f32 v36, v36, v37
	v_add_f32_e32 v1, 1.0, v1
	v_rcp_f32_e32 v38, v1
	v_mul_f32_e32 v1, 0xbfb8aa3b, v3
	v_exp_f32_e32 v1, v1
	s_nop 0
	v_add_f32_e32 v1, 1.0, v1
	v_rcp_f32_e32 v39, v1
	s_nop 0
	v_pk_mul_f32 v[2:3], v[2:3], v[38:39]
	s_nop 0
	v_cvt_pk_bf16_f32 v37, v2, v3
	v_lshl_add_u64 v[2:3], v[102:103], 0, s[12:13]
	global_store_dwordx2 v[2:3], v[36:37], off offset:512
	s_cbranch_scc1 .LBB0_605
